# scan helper pipeline made wave-local (each helper wave loads/preps/derives/builds M for its own 8-step sub-chunk, no mid-chunk barriers, loads issued two chunks ahead)
# baseline (speedup 1.0000x reference)
.LBB0_656:
	s_cmp_lg_u32 s65, 63
	s_cselect_b64 s[50:51], -1, 0
	s_cmp_eq_u32 s65, 63
	s_cbranch_scc1 .LBB0_670
.LBB0_670:
	s_cmp_eq_u32 s65, 0
	s_cbranch_scc1 .LBB0_672
	s_and_b32 s22, s64, 0x800
	v_lshl_add_u32 v21, s22, 2, v68
	v_cndmask_b32_e64 v76, v71, v70, s[4:5]
	ds_read_b128 v[72:75], v21
	v_ashrrev_i32_e32 v77, 31, v76
	v_lshl_add_u64 v[76:77], v[76:77], 0, s[40:41]
	v_lshlrev_b64 v[76:77], 12, v[76:77]
	v_lshl_add_u64 v[76:77], v[54:55], 0, v[76:77]
	s_waitcnt lgkmcnt(0)
	global_store_dwordx4 v[76:77], v[72:75], off

.Lmy_f_main:
	s_cmpk_ge_u32 s62, 0x100
	s_cbranch_scc1 .Lmy_f_hlp
	ds_read_b128 v[80:83], v225 offset:8448
	ds_read_b32 v84, v230
	ds_read_b32 v85, v230 offset:256
	ds_read_b32 v86, v230 offset:512
	ds_read_b32 v87, v230 offset:768
	ds_read_b128 v[88:91], v225
	ds_read_b128 v[92:95], v225 offset:1024
	ds_read_b128 v[96:99], v225 offset:2048
	ds_read_b128 v[100:103], v225 offset:3072
	ds_read_b32 v104, v227 offset:4
	ds_read_b32 v105, v227 offset:8
	ds_read_b32 v106, v227 offset:40
	ds_read_b32 v107, v227 offset:12
	ds_read_b32 v108, v227 offset:44
	ds_read_b32 v109, v227 offset:76
	ds_read_b32 v110, v228
	ds_read_b32 v111, v228 offset:32
	ds_read_b32 v112, v228 offset:64
	ds_read_b32 v113, v228 offset:96
	ds_read_b32 v114, v228 offset:4
	ds_read_b32 v115, v228 offset:36
	ds_read_b32 v116, v228 offset:68
	ds_read_b32 v117, v228 offset:100
	ds_read_b32 v118, v228 offset:8
	ds_read_b32 v119, v228 offset:40
	ds_read_b32 v120, v228 offset:72
	ds_read_b32 v121, v228 offset:104
	ds_read_b32 v122, v228 offset:12
	ds_read_b32 v123, v228 offset:44
	ds_read_b32 v124, v228 offset:76
	ds_read_b32 v125, v228 offset:108
	ds_read_b32 v126, v229 offset:4
	ds_read_b32 v127, v229 offset:8
	ds_read_b32 v128, v229 offset:40
	ds_read_b32 v129, v229 offset:12
	ds_read_b32 v130, v229 offset:44
	ds_read_b32 v131, v229 offset:76
	s_waitcnt lgkmcnt(15)
	v_cndmask_b32_e64 v76, 0, v84, s[98:99]
	v_cndmask_b32_e64 v77, 0, v85, s[98:99]
	v_cndmask_b32_e64 v78, 0, v86, s[98:99]
	v_cndmask_b32_e64 v79, 0, v87, s[98:99]
	v_mfma_f32_16x16x4_f32 v[240:243], v80, v76, 0
	v_mfma_f32_16x16x4_f32 v[240:243], v81, v77, v[240:243]
	v_mfma_f32_16x16x4_f32 v[240:243], v82, v78, v[240:243]
	v_mfma_f32_16x16x4_f32 v[240:243], v83, v79, v[240:243]
	v_mfma_f32_16x16x4_f32 v[240:243], v88, v208, v[240:243]
	ds_read_b128 v[184:187], v236 offset:4096
	ds_read_b128 v[188:191], v236 offset:5120
	v_mfma_f32_16x16x4_f32 v[244:247], v89, v209, 0
	ds_read_b128 v[192:195], v236 offset:6144
	ds_read_b128 v[196:199], v236 offset:7168
	v_mfma_f32_16x16x4_f32 v[240:243], v90, v210, v[240:243]
	ds_read_b128 v[132:135], v225 offset:18432
	ds_read_b32 v136, v230 offset:2048
	ds_read_b32 v137, v230 offset:2304
	v_mfma_f32_16x16x4_f32 v[244:247], v91, v211, v[244:247]
	ds_read_b32 v138, v230 offset:2560
	ds_read_b32 v139, v230 offset:2816
	ds_read_b128 v[140:143], v225 offset:9984
	v_mfma_f32_16x16x4_f32 v[240:243], v92, v212, v[240:243]
	ds_read_b128 v[144:147], v225 offset:11008
	ds_read_b128 v[148:151], v225 offset:12032
	ds_read_b128 v[152:155], v225 offset:13056
	v_mfma_f32_16x16x4_f32 v[244:247], v93, v213, v[244:247]
	ds_read_b32 v156, v227 offset:9988
	ds_read_b32 v157, v227 offset:9992
	ds_read_b32 v158, v227 offset:10024
	v_mfma_f32_16x16x4_f32 v[240:243], v94, v214, v[240:243]
	ds_read_b32 v159, v227 offset:9996
	ds_read_b32 v160, v227 offset:10028
	ds_read_b32 v161, v227 offset:10060
	v_mfma_f32_16x16x4_f32 v[244:247], v95, v215, v[244:247]
	ds_read_b32 v162, v228 offset:9984
	ds_read_b32 v163, v228 offset:10016
	ds_read_b32 v164, v228 offset:10048
	v_mfma_f32_16x16x4_f32 v[240:243], v96, v216, v[240:243]
	ds_read_b32 v165, v228 offset:10080
	ds_read_b32 v166, v228 offset:9988
	ds_read_b32 v167, v228 offset:10020
	v_mfma_f32_16x16x4_f32 v[244:247], v97, v217, v[244:247]
	ds_read_b32 v168, v228 offset:10052
	ds_read_b32 v169, v228 offset:10084
	ds_read_b32 v170, v228 offset:9992
	v_mfma_f32_16x16x4_f32 v[240:243], v98, v218, v[240:243]
	ds_read_b32 v171, v228 offset:10024
	ds_read_b32 v172, v228 offset:10056
	ds_read_b32 v173, v228 offset:10088
	v_mfma_f32_16x16x4_f32 v[244:247], v99, v219, v[244:247]
	ds_read_b32 v174, v228 offset:9996
	ds_read_b32 v175, v228 offset:10028
	ds_read_b32 v176, v228 offset:10060
	v_mfma_f32_16x16x4_f32 v[240:243], v100, v220, v[240:243]
	ds_read_b32 v177, v228 offset:10092
	ds_read_b32 v178, v229 offset:9988
	ds_read_b32 v179, v229 offset:9992
	v_mfma_f32_16x16x4_f32 v[244:247], v101, v221, v[244:247]
	ds_read_b32 v180, v229 offset:10024
	ds_read_b32 v181, v229 offset:9996
	ds_read_b32 v182, v229 offset:10028
	v_mfma_f32_16x16x4_f32 v[240:243], v102, v222, v[240:243]
	ds_read_b32 v183, v229 offset:10060
	v_mfma_f32_16x16x4_f32 v[244:247], v103, v223, v[244:247]
	s_nop 9
	v_add_f32_e32 v240, v240, v244
	v_add_f32_e32 v241, v241, v245
	v_add_f32_e32 v242, v242, v246
	v_add_f32_e32 v243, v243, v247
	v_fmac_f32_e32 v241, v104, v240
	v_fmac_f32_e32 v242, v105, v240
	v_fmac_f32_e32 v242, v106, v241
	v_fmac_f32_e32 v243, v107, v240
	v_fmac_f32_e32 v243, v108, v241
	v_fmac_f32_e32 v243, v109, v242
	ds_bpermute_b32 v204, v232, v240
	ds_bpermute_b32 v205, v232, v241
	ds_bpermute_b32 v206, v232, v242
	ds_bpermute_b32 v207, v232, v243
	ds_read_b128 v[88:91], v226
	ds_read_b128 v[92:95], v226 offset:64
	ds_read_b128 v[96:99], v226 offset:128
	ds_read_b128 v[100:103], v226 offset:192
	s_waitcnt lgkmcnt(15)
	v_cndmask_b32_e64 v76, 0, v136, s[98:99]
	v_cndmask_b32_e64 v77, 0, v137, s[98:99]
	v_cndmask_b32_e64 v78, 0, v138, s[98:99]
	v_cndmask_b32_e64 v79, 0, v139, s[98:99]
	v_mfma_f32_16x16x4_f32 v[72:75], v132, v76, 0
	s_waitcnt lgkmcnt(7)
	v_fmac_f32_e32 v240, v110, v204
	s_waitcnt lgkmcnt(6)
	v_fmac_f32_e32 v240, v111, v205
	s_waitcnt lgkmcnt(5)
	v_fmac_f32_e32 v240, v112, v206
	s_waitcnt lgkmcnt(4)
	v_fmac_f32_e32 v240, v113, v207
	v_fmac_f32_e32 v241, v114, v204
	v_fmac_f32_e32 v241, v115, v205
	v_mfma_f32_16x16x4_f32 v[72:75], v133, v77, v[72:75]
	v_fmac_f32_e32 v241, v116, v206
	v_fmac_f32_e32 v241, v117, v207
	v_fmac_f32_e32 v242, v118, v204
	v_fmac_f32_e32 v242, v119, v205
	v_fmac_f32_e32 v242, v120, v206
	v_fmac_f32_e32 v242, v121, v207
	v_mfma_f32_16x16x4_f32 v[72:75], v134, v78, v[72:75]
	v_fmac_f32_e32 v243, v122, v204
	v_fmac_f32_e32 v243, v123, v205
	v_fmac_f32_e32 v243, v124, v206
	v_fmac_f32_e32 v243, v125, v207
	v_mfma_f32_16x16x4_f32 v[72:75], v135, v79, v[72:75]
	v_fmac_f32_e32 v241, v126, v240
	v_fmac_f32_e32 v242, v127, v240
	v_fmac_f32_e32 v242, v128, v241
	v_fmac_f32_e32 v243, v129, v240
	v_fmac_f32_e32 v243, v130, v241
	v_fmac_f32_e32 v243, v131, v242
	v_cndmask_b32_e64 v200, v240, v84, s[98:99]
	v_cndmask_b32_e64 v201, v241, v85, s[98:99]
	v_cndmask_b32_e64 v202, v242, v86, s[98:99]
	v_cndmask_b32_e64 v203, v243, v87, s[98:99]
	v_cndmask_b32_e64 v252, v240, 0, s[98:99]
	v_cndmask_b32_e64 v253, v241, 0, s[98:99]
	v_cndmask_b32_e64 v254, v242, 0, s[98:99]
	v_cndmask_b32_e64 v255, v243, 0, s[98:99]
	v_mfma_f32_16x16x4_f32 v[208:211], v184, v200, v[208:211]
	v_mfma_f32_16x16x4_f32 v[212:215], v188, v200, v[212:215]
	v_mfma_f32_16x16x4_f32 v[216:219], v192, v200, v[216:219]
	v_mfma_f32_16x16x4_f32 v[220:223], v196, v200, v[220:223]
	v_mfma_f32_16x16x4_f32 v[208:211], v185, v201, v[208:211]
	v_mfma_f32_16x16x4_f32 v[212:215], v189, v201, v[212:215]
	v_mfma_f32_16x16x4_f32 v[216:219], v193, v201, v[216:219]
	v_mfma_f32_16x16x4_f32 v[220:223], v197, v201, v[220:223]
	v_mfma_f32_16x16x4_f32 v[208:211], v186, v202, v[208:211]
	v_mfma_f32_16x16x4_f32 v[212:215], v190, v202, v[212:215]
	v_mfma_f32_16x16x4_f32 v[216:219], v194, v202, v[216:219]
	v_mfma_f32_16x16x4_f32 v[220:223], v198, v202, v[220:223]
	v_mfma_f32_16x16x4_f32 v[208:211], v187, v203, v[208:211]
	v_mfma_f32_16x16x4_f32 v[212:215], v191, v203, v[212:215]
	v_mfma_f32_16x16x4_f32 v[216:219], v195, v203, v[216:219]
	v_mfma_f32_16x16x4_f32 v[220:223], v199, v203, v[220:223]
	v_mfma_f32_16x16x4_f32 v[248:251], v80, v252, v[240:243]
	v_mfma_f32_16x16x4_f32 v[248:251], v81, v253, v[248:251]
	v_mfma_f32_16x16x4_f32 v[248:251], v82, v254, v[248:251]
	v_mfma_f32_16x16x4_f32 v[248:251], v83, v255, v[248:251]
	s_waitcnt lgkmcnt(3)
	s_nop 2
	v_mul_f32_e32 v208, v208, v88
	v_mul_f32_e32 v209, v209, v89
	v_mul_f32_e32 v210, v210, v90
	v_mul_f32_e32 v211, v211, v91
	v_mfma_f32_16x16x4_f32 v[72:75], v140, v208, v[72:75]
	s_waitcnt lgkmcnt(2)
	v_mul_f32_e32 v212, v212, v92
	v_mul_f32_e32 v213, v213, v93
	v_mfma_f32_16x16x4_f32 v[244:247], v141, v209, 0
	v_mul_f32_e32 v214, v214, v94
	v_mul_f32_e32 v215, v215, v95
	v_mfma_f32_16x16x4_f32 v[72:75], v142, v210, v[72:75]
	s_waitcnt lgkmcnt(1)
	v_mul_f32_e32 v216, v216, v96
	v_mul_f32_e32 v217, v217, v97
	v_mfma_f32_16x16x4_f32 v[244:247], v143, v211, v[244:247]
	v_mul_f32_e32 v218, v218, v98
	v_mul_f32_e32 v219, v219, v99
	v_mfma_f32_16x16x4_f32 v[72:75], v144, v212, v[72:75]
	s_waitcnt lgkmcnt(0)
	v_mul_f32_e32 v220, v220, v100
	v_mul_f32_e32 v221, v221, v101
	v_mfma_f32_16x16x4_f32 v[244:247], v145, v213, v[244:247]
	v_mul_f32_e32 v222, v222, v102
	v_mul_f32_e32 v223, v223, v103
	v_mfma_f32_16x16x4_f32 v[72:75], v146, v214, v[72:75]
	s_mov_b64 exec, s[98:99]
	ds_write_b32 v231, v248
	ds_write_b32 v231, v249 offset:256
	ds_write_b32 v231, v250 offset:512
	ds_write_b32 v231, v251 offset:768
	s_mov_b64 exec, -1
	ds_read_b128 v[184:187], v236 offset:14080
	ds_read_b128 v[188:191], v236 offset:15104
	v_mfma_f32_16x16x4_f32 v[244:247], v147, v215, v[244:247]
	ds_read_b128 v[192:195], v236 offset:16128
	ds_read_b128 v[196:199], v236 offset:17152
	v_mfma_f32_16x16x4_f32 v[72:75], v148, v216, v[72:75]
	v_mfma_f32_16x16x4_f32 v[244:247], v149, v217, v[244:247]
	v_mfma_f32_16x16x4_f32 v[72:75], v150, v218, v[72:75]
	v_mfma_f32_16x16x4_f32 v[244:247], v151, v219, v[244:247]
	v_mfma_f32_16x16x4_f32 v[72:75], v152, v220, v[72:75]
	v_mfma_f32_16x16x4_f32 v[244:247], v153, v221, v[244:247]
	v_mfma_f32_16x16x4_f32 v[72:75], v154, v222, v[72:75]
	v_mfma_f32_16x16x4_f32 v[244:247], v155, v223, v[244:247]
	s_nop 9
	v_add_f32_e32 v72, v72, v244
	v_add_f32_e32 v73, v73, v245
	v_add_f32_e32 v74, v74, v246
	v_add_f32_e32 v75, v75, v247
	v_fmac_f32_e32 v73, v156, v72
	v_fmac_f32_e32 v74, v157, v72
	v_fmac_f32_e32 v74, v158, v73
	v_fmac_f32_e32 v75, v159, v72
	v_fmac_f32_e32 v75, v160, v73
	v_fmac_f32_e32 v75, v161, v74
	ds_bpermute_b32 v204, v232, v72
	ds_bpermute_b32 v205, v232, v73
	ds_bpermute_b32 v206, v232, v74
	ds_bpermute_b32 v207, v232, v75
	ds_read_b128 v[140:143], v226 offset:9984
	ds_read_b128 v[144:147], v226 offset:10048
	ds_read_b128 v[148:151], v226 offset:10112
	ds_read_b128 v[152:155], v226 offset:10176
	s_waitcnt lgkmcnt(7)
	v_fmac_f32_e32 v72, v162, v204
	s_waitcnt lgkmcnt(6)
	v_fmac_f32_e32 v72, v163, v205
	s_waitcnt lgkmcnt(5)
	v_fmac_f32_e32 v72, v164, v206
	s_waitcnt lgkmcnt(4)
	v_fmac_f32_e32 v72, v165, v207
	v_fmac_f32_e32 v73, v166, v204
	v_fmac_f32_e32 v73, v167, v205
	v_fmac_f32_e32 v73, v168, v206
	v_fmac_f32_e32 v73, v169, v207
	v_fmac_f32_e32 v74, v170, v204
	v_fmac_f32_e32 v74, v171, v205
	v_fmac_f32_e32 v74, v172, v206
	v_fmac_f32_e32 v74, v173, v207
	v_fmac_f32_e32 v75, v174, v204
	v_fmac_f32_e32 v75, v175, v205
	v_fmac_f32_e32 v75, v176, v206
	v_fmac_f32_e32 v75, v177, v207
	v_fmac_f32_e32 v73, v178, v72
	v_fmac_f32_e32 v74, v179, v72
	v_fmac_f32_e32 v74, v180, v73
	v_fmac_f32_e32 v75, v181, v72
	v_fmac_f32_e32 v75, v182, v73
	v_fmac_f32_e32 v75, v183, v74
	v_cndmask_b32_e64 v200, v72, v136, s[98:99]
	v_cndmask_b32_e64 v201, v73, v137, s[98:99]
	v_cndmask_b32_e64 v202, v74, v138, s[98:99]
	v_cndmask_b32_e64 v203, v75, v139, s[98:99]
	v_cndmask_b32_e64 v252, v72, 0, s[98:99]
	v_cndmask_b32_e64 v253, v73, 0, s[98:99]
	v_cndmask_b32_e64 v254, v74, 0, s[98:99]
	v_cndmask_b32_e64 v255, v75, 0, s[98:99]
	v_mfma_f32_16x16x4_f32 v[208:211], v184, v200, v[208:211]
	v_mfma_f32_16x16x4_f32 v[212:215], v188, v200, v[212:215]
	v_mfma_f32_16x16x4_f32 v[216:219], v192, v200, v[216:219]
	v_mfma_f32_16x16x4_f32 v[220:223], v196, v200, v[220:223]
	v_mfma_f32_16x16x4_f32 v[208:211], v185, v201, v[208:211]
	v_mfma_f32_16x16x4_f32 v[212:215], v189, v201, v[212:215]
	v_mfma_f32_16x16x4_f32 v[216:219], v193, v201, v[216:219]
	v_mfma_f32_16x16x4_f32 v[220:223], v197, v201, v[220:223]
	v_mfma_f32_16x16x4_f32 v[208:211], v186, v202, v[208:211]
	v_mfma_f32_16x16x4_f32 v[212:215], v190, v202, v[212:215]
	v_mfma_f32_16x16x4_f32 v[216:219], v194, v202, v[216:219]
	v_mfma_f32_16x16x4_f32 v[220:223], v198, v202, v[220:223]
	v_mfma_f32_16x16x4_f32 v[208:211], v187, v203, v[208:211]
	v_mfma_f32_16x16x4_f32 v[212:215], v191, v203, v[212:215]
	v_mfma_f32_16x16x4_f32 v[216:219], v195, v203, v[216:219]
	v_mfma_f32_16x16x4_f32 v[220:223], v199, v203, v[220:223]
	v_mfma_f32_16x16x4_f32 v[248:251], v132, v252, v[72:75]
	v_mfma_f32_16x16x4_f32 v[248:251], v133, v253, v[248:251]
	v_mfma_f32_16x16x4_f32 v[248:251], v134, v254, v[248:251]
	v_mfma_f32_16x16x4_f32 v[248:251], v135, v255, v[248:251]
	s_mov_b32 s100, 0x6100
	s_cmp_eq_u32 s23, 0
	s_cselect_b32 s100, s100, 0x4e00
	v_add_u32_e32 v225, s100, v225
	v_add_u32_e32 v236, s100, v236
	v_add_u32_e32 v226, s100, v226
	v_add_u32_e32 v227, s100, v227
	v_add_u32_e32 v228, s100, v228
	v_add_u32_e32 v229, s100, v229
	ds_read_b128 v[80:83], v225 offset:8448
	ds_read_b32 v84, v230 offset:4096
	ds_read_b32 v85, v230 offset:4352
	ds_read_b32 v86, v230 offset:4608
	ds_read_b32 v87, v230 offset:4864
	ds_read_b128 v[88:91], v225
	ds_read_b128 v[92:95], v225 offset:1024
	ds_read_b128 v[96:99], v225 offset:2048
	ds_read_b128 v[100:103], v225 offset:3072
	ds_read_b32 v104, v227 offset:4
	ds_read_b32 v105, v227 offset:8
	ds_read_b32 v106, v227 offset:40
	ds_read_b32 v107, v227 offset:12
	ds_read_b32 v108, v227 offset:44
	ds_read_b32 v109, v227 offset:76
	ds_read_b32 v110, v228
	ds_read_b32 v111, v228 offset:32
	ds_read_b32 v112, v228 offset:64
	ds_read_b32 v113, v228 offset:96
	ds_read_b32 v114, v228 offset:4
	ds_read_b32 v115, v228 offset:36
	ds_read_b32 v116, v228 offset:68
	ds_read_b32 v117, v228 offset:100
	ds_read_b32 v118, v228 offset:8
	ds_read_b32 v119, v228 offset:40
	ds_read_b32 v120, v228 offset:72
	ds_read_b32 v121, v228 offset:104
	ds_read_b32 v122, v228 offset:12
	ds_read_b32 v123, v228 offset:44
	ds_read_b32 v124, v228 offset:76
	ds_read_b32 v125, v228 offset:108
	ds_read_b32 v126, v229 offset:4
	ds_read_b32 v127, v229 offset:8
	ds_read_b32 v128, v229 offset:40
	ds_read_b32 v129, v229 offset:12
	ds_read_b32 v130, v229 offset:44
	ds_read_b32 v131, v229 offset:76
	s_waitcnt lgkmcnt(15)
	v_cndmask_b32_e64 v76, 0, v84, s[98:99]
	v_cndmask_b32_e64 v77, 0, v85, s[98:99]
	v_cndmask_b32_e64 v78, 0, v86, s[98:99]
	v_cndmask_b32_e64 v79, 0, v87, s[98:99]
	v_mfma_f32_16x16x4_f32 v[240:243], v80, v76, 0
	v_mfma_f32_16x16x4_f32 v[240:243], v81, v77, v[240:243]
	v_mfma_f32_16x16x4_f32 v[240:243], v82, v78, v[240:243]
	v_mfma_f32_16x16x4_f32 v[240:243], v83, v79, v[240:243]
	v_mul_f32_e32 v208, v208, v140
	v_mul_f32_e32 v209, v209, v141
	v_mul_f32_e32 v210, v210, v142
	v_mul_f32_e32 v211, v211, v143
	v_mfma_f32_16x16x4_f32 v[240:243], v88, v208, v[240:243]
	v_mul_f32_e32 v212, v212, v144
	v_mul_f32_e32 v213, v213, v145
	v_mfma_f32_16x16x4_f32 v[244:247], v89, v209, 0
	v_mul_f32_e32 v214, v214, v146
	v_mul_f32_e32 v215, v215, v147
	v_mfma_f32_16x16x4_f32 v[240:243], v90, v210, v[240:243]
	v_mul_f32_e32 v216, v216, v148
	v_mul_f32_e32 v217, v217, v149
	v_mfma_f32_16x16x4_f32 v[244:247], v91, v211, v[244:247]
	v_mul_f32_e32 v218, v218, v150
	v_mul_f32_e32 v219, v219, v151
	v_mfma_f32_16x16x4_f32 v[240:243], v92, v212, v[240:243]
	v_mul_f32_e32 v220, v220, v152
	v_mul_f32_e32 v221, v221, v153
	v_mfma_f32_16x16x4_f32 v[244:247], v93, v213, v[244:247]
	v_mul_f32_e32 v222, v222, v154
	v_mul_f32_e32 v223, v223, v155
	v_mfma_f32_16x16x4_f32 v[240:243], v94, v214, v[240:243]
	s_mov_b64 exec, s[98:99]
	ds_write_b32 v231, v248 offset:2048
	ds_write_b32 v231, v249 offset:2304
	ds_write_b32 v231, v250 offset:2560
	ds_write_b32 v231, v251 offset:2816
	s_mov_b64 exec, -1
	ds_read_b128 v[184:187], v236 offset:4096
	ds_read_b128 v[188:191], v236 offset:5120
	v_mfma_f32_16x16x4_f32 v[244:247], v95, v215, v[244:247]
	ds_read_b128 v[192:195], v236 offset:6144
	ds_read_b128 v[196:199], v236 offset:7168
	v_mfma_f32_16x16x4_f32 v[240:243], v96, v216, v[240:243]
	ds_read_b128 v[132:135], v225 offset:18432
	ds_read_b32 v136, v230 offset:6144
	ds_read_b32 v137, v230 offset:6400
	ds_read_b32 v138, v230 offset:6656
	ds_read_b32 v139, v230 offset:6912
	v_mfma_f32_16x16x4_f32 v[244:247], v97, v217, v[244:247]
	ds_read_b128 v[140:143], v225 offset:9984
	ds_read_b128 v[144:147], v225 offset:11008
	ds_read_b128 v[148:151], v225 offset:12032
	ds_read_b128 v[152:155], v225 offset:13056
	ds_read_b32 v156, v227 offset:9988
	v_mfma_f32_16x16x4_f32 v[240:243], v98, v218, v[240:243]
	ds_read_b32 v157, v227 offset:9992
	ds_read_b32 v158, v227 offset:10024
	ds_read_b32 v159, v227 offset:9996
	ds_read_b32 v160, v227 offset:10028
	ds_read_b32 v161, v227 offset:10060
	v_mfma_f32_16x16x4_f32 v[244:247], v99, v219, v[244:247]
	ds_read_b32 v162, v228 offset:9984
	ds_read_b32 v163, v228 offset:10016
	ds_read_b32 v164, v228 offset:10048
	ds_read_b32 v165, v228 offset:10080
	ds_read_b32 v166, v228 offset:9988
	v_mfma_f32_16x16x4_f32 v[240:243], v100, v220, v[240:243]
	ds_read_b32 v167, v228 offset:10020
	ds_read_b32 v168, v228 offset:10052
	ds_read_b32 v169, v228 offset:10084
	ds_read_b32 v170, v228 offset:9992
	ds_read_b32 v171, v228 offset:10024
	v_mfma_f32_16x16x4_f32 v[244:247], v101, v221, v[244:247]
	ds_read_b32 v172, v228 offset:10056
	ds_read_b32 v173, v228 offset:10088
	ds_read_b32 v174, v228 offset:9996
	ds_read_b32 v175, v228 offset:10028
	ds_read_b32 v176, v228 offset:10060
	v_mfma_f32_16x16x4_f32 v[240:243], v102, v222, v[240:243]
	ds_read_b32 v177, v228 offset:10092
	ds_read_b32 v178, v229 offset:9988
	ds_read_b32 v179, v229 offset:9992
	ds_read_b32 v180, v229 offset:10024
	ds_read_b32 v181, v229 offset:9996
	v_mfma_f32_16x16x4_f32 v[244:247], v103, v223, v[244:247]
	ds_read_b32 v182, v229 offset:10028
	ds_read_b32 v183, v229 offset:10060
	s_nop 7
	v_add_f32_e32 v240, v240, v244
	v_add_f32_e32 v241, v241, v245
	v_add_f32_e32 v242, v242, v246
	v_add_f32_e32 v243, v243, v247
	v_fmac_f32_e32 v241, v104, v240
	v_fmac_f32_e32 v242, v105, v240
	v_fmac_f32_e32 v242, v106, v241
	v_fmac_f32_e32 v243, v107, v240
	v_fmac_f32_e32 v243, v108, v241
	v_fmac_f32_e32 v243, v109, v242
	ds_bpermute_b32 v204, v232, v240
	ds_bpermute_b32 v205, v232, v241
	ds_bpermute_b32 v206, v232, v242
	ds_bpermute_b32 v207, v232, v243
	ds_read_b128 v[88:91], v226
	ds_read_b128 v[92:95], v226 offset:64
	ds_read_b128 v[96:99], v226 offset:128
	ds_read_b128 v[100:103], v226 offset:192
	s_waitcnt lgkmcnt(15)
	v_cndmask_b32_e64 v76, 0, v136, s[98:99]
	v_cndmask_b32_e64 v77, 0, v137, s[98:99]
	v_cndmask_b32_e64 v78, 0, v138, s[98:99]
	v_cndmask_b32_e64 v79, 0, v139, s[98:99]
	v_mfma_f32_16x16x4_f32 v[72:75], v132, v76, 0
	s_waitcnt lgkmcnt(7)
	v_fmac_f32_e32 v240, v110, v204
	s_waitcnt lgkmcnt(6)
	v_fmac_f32_e32 v240, v111, v205
	s_waitcnt lgkmcnt(5)
	v_fmac_f32_e32 v240, v112, v206
	s_waitcnt lgkmcnt(4)
	v_fmac_f32_e32 v240, v113, v207
	v_fmac_f32_e32 v241, v114, v204
	v_fmac_f32_e32 v241, v115, v205
	v_mfma_f32_16x16x4_f32 v[72:75], v133, v77, v[72:75]
	v_fmac_f32_e32 v241, v116, v206
	v_fmac_f32_e32 v241, v117, v207
	v_fmac_f32_e32 v242, v118, v204
	v_fmac_f32_e32 v242, v119, v205
	v_fmac_f32_e32 v242, v120, v206
	v_fmac_f32_e32 v242, v121, v207
	v_mfma_f32_16x16x4_f32 v[72:75], v134, v78, v[72:75]
	v_fmac_f32_e32 v243, v122, v204
	v_fmac_f32_e32 v243, v123, v205
	v_fmac_f32_e32 v243, v124, v206
	v_fmac_f32_e32 v243, v125, v207
	v_mfma_f32_16x16x4_f32 v[72:75], v135, v79, v[72:75]
	v_fmac_f32_e32 v241, v126, v240
	v_fmac_f32_e32 v242, v127, v240
	v_fmac_f32_e32 v242, v128, v241
	v_fmac_f32_e32 v243, v129, v240
	v_fmac_f32_e32 v243, v130, v241
	v_fmac_f32_e32 v243, v131, v242
	v_cndmask_b32_e64 v200, v240, v84, s[98:99]
	v_cndmask_b32_e64 v201, v241, v85, s[98:99]
	v_cndmask_b32_e64 v202, v242, v86, s[98:99]
	v_cndmask_b32_e64 v203, v243, v87, s[98:99]
	v_cndmask_b32_e64 v252, v240, 0, s[98:99]
	v_cndmask_b32_e64 v253, v241, 0, s[98:99]
	v_cndmask_b32_e64 v254, v242, 0, s[98:99]
	v_cndmask_b32_e64 v255, v243, 0, s[98:99]
	v_mfma_f32_16x16x4_f32 v[208:211], v184, v200, v[208:211]
	v_mfma_f32_16x16x4_f32 v[212:215], v188, v200, v[212:215]
	v_mfma_f32_16x16x4_f32 v[216:219], v192, v200, v[216:219]
	v_mfma_f32_16x16x4_f32 v[220:223], v196, v200, v[220:223]
	v_mfma_f32_16x16x4_f32 v[208:211], v185, v201, v[208:211]
	v_mfma_f32_16x16x4_f32 v[212:215], v189, v201, v[212:215]
	v_mfma_f32_16x16x4_f32 v[216:219], v193, v201, v[216:219]
	v_mfma_f32_16x16x4_f32 v[220:223], v197, v201, v[220:223]
	v_mfma_f32_16x16x4_f32 v[208:211], v186, v202, v[208:211]
	v_mfma_f32_16x16x4_f32 v[212:215], v190, v202, v[212:215]
	v_mfma_f32_16x16x4_f32 v[216:219], v194, v202, v[216:219]
	v_mfma_f32_16x16x4_f32 v[220:223], v198, v202, v[220:223]
	v_mfma_f32_16x16x4_f32 v[208:211], v187, v203, v[208:211]
	v_mfma_f32_16x16x4_f32 v[212:215], v191, v203, v[212:215]
	v_mfma_f32_16x16x4_f32 v[216:219], v195, v203, v[216:219]
	v_mfma_f32_16x16x4_f32 v[220:223], v199, v203, v[220:223]
	v_mfma_f32_16x16x4_f32 v[248:251], v80, v252, v[240:243]
	v_mfma_f32_16x16x4_f32 v[248:251], v81, v253, v[248:251]
	v_mfma_f32_16x16x4_f32 v[248:251], v82, v254, v[248:251]
	v_mfma_f32_16x16x4_f32 v[248:251], v83, v255, v[248:251]
	s_waitcnt lgkmcnt(3)
	s_nop 2
	v_mul_f32_e32 v208, v208, v88
	v_mul_f32_e32 v209, v209, v89
	v_mul_f32_e32 v210, v210, v90
	v_mul_f32_e32 v211, v211, v91
	v_mfma_f32_16x16x4_f32 v[72:75], v140, v208, v[72:75]
	s_waitcnt lgkmcnt(2)
	v_mul_f32_e32 v212, v212, v92
	v_mul_f32_e32 v213, v213, v93
	v_mfma_f32_16x16x4_f32 v[244:247], v141, v209, 0
	v_mul_f32_e32 v214, v214, v94
	v_mul_f32_e32 v215, v215, v95
	v_mfma_f32_16x16x4_f32 v[72:75], v142, v210, v[72:75]
	s_waitcnt lgkmcnt(1)
	v_mul_f32_e32 v216, v216, v96
	v_mul_f32_e32 v217, v217, v97
	v_mfma_f32_16x16x4_f32 v[244:247], v143, v211, v[244:247]
	v_mul_f32_e32 v218, v218, v98
	v_mul_f32_e32 v219, v219, v99
	v_mfma_f32_16x16x4_f32 v[72:75], v144, v212, v[72:75]
	s_waitcnt lgkmcnt(0)
	v_mul_f32_e32 v220, v220, v100
	v_mul_f32_e32 v221, v221, v101
	v_mfma_f32_16x16x4_f32 v[244:247], v145, v213, v[244:247]
	v_mul_f32_e32 v222, v222, v102
	v_mul_f32_e32 v223, v223, v103
	v_mfma_f32_16x16x4_f32 v[72:75], v146, v214, v[72:75]
	s_mov_b64 exec, s[98:99]
	ds_write_b32 v231, v248 offset:4096
	ds_write_b32 v231, v249 offset:4352
	ds_write_b32 v231, v250 offset:4608
	ds_write_b32 v231, v251 offset:4864
	s_mov_b64 exec, -1
	ds_read_b128 v[184:187], v236 offset:14080
	ds_read_b128 v[188:191], v236 offset:15104
	v_mfma_f32_16x16x4_f32 v[244:247], v147, v215, v[244:247]
	ds_read_b128 v[192:195], v236 offset:16128
	ds_read_b128 v[196:199], v236 offset:17152
	v_mfma_f32_16x16x4_f32 v[72:75], v148, v216, v[72:75]
	v_mfma_f32_16x16x4_f32 v[244:247], v149, v217, v[244:247]
	v_mfma_f32_16x16x4_f32 v[72:75], v150, v218, v[72:75]
	v_mfma_f32_16x16x4_f32 v[244:247], v151, v219, v[244:247]
	v_mfma_f32_16x16x4_f32 v[72:75], v152, v220, v[72:75]
	v_mfma_f32_16x16x4_f32 v[244:247], v153, v221, v[244:247]
	v_mfma_f32_16x16x4_f32 v[72:75], v154, v222, v[72:75]
	v_mfma_f32_16x16x4_f32 v[244:247], v155, v223, v[244:247]
	s_nop 9
	v_add_f32_e32 v72, v72, v244
	v_add_f32_e32 v73, v73, v245
	v_add_f32_e32 v74, v74, v246
	v_add_f32_e32 v75, v75, v247
	v_fmac_f32_e32 v73, v156, v72
	v_fmac_f32_e32 v74, v157, v72
	v_fmac_f32_e32 v74, v158, v73
	v_fmac_f32_e32 v75, v159, v72
	v_fmac_f32_e32 v75, v160, v73
	v_fmac_f32_e32 v75, v161, v74
	ds_bpermute_b32 v204, v232, v72
	ds_bpermute_b32 v205, v232, v73
	ds_bpermute_b32 v206, v232, v74
	ds_bpermute_b32 v207, v232, v75
	ds_read_b128 v[140:143], v226 offset:9984
	ds_read_b128 v[144:147], v226 offset:10048
	ds_read_b128 v[148:151], v226 offset:10112
	ds_read_b128 v[152:155], v226 offset:10176
	s_waitcnt lgkmcnt(7)
	v_fmac_f32_e32 v72, v162, v204
	s_waitcnt lgkmcnt(6)
	v_fmac_f32_e32 v72, v163, v205
	s_waitcnt lgkmcnt(5)
	v_fmac_f32_e32 v72, v164, v206
	s_waitcnt lgkmcnt(4)
	v_fmac_f32_e32 v72, v165, v207
	v_fmac_f32_e32 v73, v166, v204
	v_fmac_f32_e32 v73, v167, v205
	v_fmac_f32_e32 v73, v168, v206
	v_fmac_f32_e32 v73, v169, v207
	v_fmac_f32_e32 v74, v170, v204
	v_fmac_f32_e32 v74, v171, v205
	v_fmac_f32_e32 v74, v172, v206
	v_fmac_f32_e32 v74, v173, v207
	v_fmac_f32_e32 v75, v174, v204
	v_fmac_f32_e32 v75, v175, v205
	v_fmac_f32_e32 v75, v176, v206
	v_fmac_f32_e32 v75, v177, v207
	v_fmac_f32_e32 v73, v178, v72
	v_fmac_f32_e32 v74, v179, v72
	v_fmac_f32_e32 v74, v180, v73
	v_fmac_f32_e32 v75, v181, v72
	v_fmac_f32_e32 v75, v182, v73
	v_fmac_f32_e32 v75, v183, v74
	v_cndmask_b32_e64 v200, v72, v136, s[98:99]
	v_cndmask_b32_e64 v201, v73, v137, s[98:99]
	v_cndmask_b32_e64 v202, v74, v138, s[98:99]
	v_cndmask_b32_e64 v203, v75, v139, s[98:99]
	v_cndmask_b32_e64 v252, v72, 0, s[98:99]
	v_cndmask_b32_e64 v253, v73, 0, s[98:99]
	v_cndmask_b32_e64 v254, v74, 0, s[98:99]
	v_cndmask_b32_e64 v255, v75, 0, s[98:99]
	v_mfma_f32_16x16x4_f32 v[208:211], v184, v200, v[208:211]
	v_mfma_f32_16x16x4_f32 v[212:215], v188, v200, v[212:215]
	v_mfma_f32_16x16x4_f32 v[216:219], v192, v200, v[216:219]
	v_mfma_f32_16x16x4_f32 v[220:223], v196, v200, v[220:223]
	v_mfma_f32_16x16x4_f32 v[208:211], v185, v201, v[208:211]
	v_mfma_f32_16x16x4_f32 v[212:215], v189, v201, v[212:215]
	v_mfma_f32_16x16x4_f32 v[216:219], v193, v201, v[216:219]
	v_mfma_f32_16x16x4_f32 v[220:223], v197, v201, v[220:223]
	v_mfma_f32_16x16x4_f32 v[208:211], v186, v202, v[208:211]
	v_mfma_f32_16x16x4_f32 v[212:215], v190, v202, v[212:215]
	v_mfma_f32_16x16x4_f32 v[216:219], v194, v202, v[216:219]
	v_mfma_f32_16x16x4_f32 v[220:223], v198, v202, v[220:223]
	v_mfma_f32_16x16x4_f32 v[208:211], v187, v203, v[208:211]
	v_mfma_f32_16x16x4_f32 v[212:215], v191, v203, v[212:215]
	v_mfma_f32_16x16x4_f32 v[216:219], v195, v203, v[216:219]
	v_mfma_f32_16x16x4_f32 v[220:223], v199, v203, v[220:223]
	v_mfma_f32_16x16x4_f32 v[248:251], v132, v252, v[72:75]
	v_mfma_f32_16x16x4_f32 v[248:251], v133, v253, v[248:251]
	v_mfma_f32_16x16x4_f32 v[248:251], v134, v254, v[248:251]
	v_mfma_f32_16x16x4_f32 v[248:251], v135, v255, v[248:251]
	s_waitcnt lgkmcnt(3)
	s_nop 2
	v_mul_f32_e32 v208, v208, v140
	v_mul_f32_e32 v209, v209, v141
	v_mul_f32_e32 v210, v210, v142
	v_mul_f32_e32 v211, v211, v143
	s_waitcnt lgkmcnt(2)
	v_mul_f32_e32 v212, v212, v144
	v_mul_f32_e32 v213, v213, v145
	v_mul_f32_e32 v214, v214, v146
	v_mul_f32_e32 v215, v215, v147
	s_waitcnt lgkmcnt(1)
	v_mul_f32_e32 v216, v216, v148
	v_mul_f32_e32 v217, v217, v149
	v_mul_f32_e32 v218, v218, v150
	v_mul_f32_e32 v219, v219, v151
	s_waitcnt lgkmcnt(0)
	v_mul_f32_e32 v220, v220, v152
	v_mul_f32_e32 v221, v221, v153
	v_mul_f32_e32 v222, v222, v154
	v_mul_f32_e32 v223, v223, v155
	s_mov_b64 exec, s[98:99]
	ds_write_b32 v231, v248 offset:6144
	ds_write_b32 v231, v249 offset:6400
	ds_write_b32 v231, v250 offset:6656
	ds_write_b32 v231, v251 offset:6912
	s_mov_b64 exec, -1
	s_branch .LBB0_655
.Lmy_f_hlp:
	s_cmp_eq_u32 s65, 63
	s_cbranch_scc0 .Lmy_f_hl2
	s_branch .LBB0_655
.Lmy_f_hl2:
	s_bfe_u32 s100, s62, 0x20006
	s_lshl_b32 s100, s100, 2
	s_add_i32 s101, s100, -16
	s_add_i32 s100, s100, -12
	s_cmp_lg_u32 s65, 0
	s_cbranch_scc1 .Lmy_f_nol2
	v_add_u32_e32 v70, s101, v70
	v_subrev_u32_e32 v71, s101, v71
	v_add_u32_e32 v21, 64, v70
	v_subrev_u32_e32 v26, 64, v71
	v_cndmask_b32_e64 v32, v26, v21, s[4:5]
	v_ashrrev_i32_e32 v33, 31, v32
	v_lshl_add_u64 v[44:45], v[32:33], 0, s[40:41]
	v_mad_u64_u32 v[46:47], s[96:97], v44, s56, v[50:51]
	v_mad_i32_i24 v47, v45, s56, v47
	global_load_dwordx2 v[26:27], v[46:47], off
	v_mov_b32_e32 v30, v20
	v_mov_b32_e32 v31, v20
	v_cmp_lt_i32_e64 s[96:97], 0, v32
	v_mov_b64_e32 v[28:29], v[30:31]
	s_and_saveexec_b64 s[24:25], s[96:97]
	s_cbranch_execz .Lmy_f_k659
	v_add_co_u32_e32 v28, vcc, 0xfffff000, v46
	s_nop 1
	v_addc_co_u32_e32 v29, vcc, -1, v47, vcc
	global_load_dwordx2 v[28:29], v[28:29], off offset:-2048

.Lmy_f_k669:
	s_or_b64 exec, exec, s[96:97]
	v_lshlrev_b64 v[44:45], 13, v[44:45]
	v_lshl_add_u64 v[44:45], v[52:53], 0, v[44:45]
	v_add_co_u32_e32 v46, vcc, 0x1000, v44
	s_nop 1
	v_addc_co_u32_e32 v47, vcc, 0, v45, vcc
	global_load_dwordx2 v[44:45], v[44:45], off
	s_nop 0
	global_load_dwordx2 v[46:47], v[46:47], off
	v_subrev_u32_e32 v70, s101, v70
	v_add_u32_e32 v71, s101, v71
	v_add_u32_e32 v70, s100, v70
	v_subrev_u32_e32 v71, s100, v71
	v_add_u32_e32 v21, 64, v70
	v_subrev_u32_e32 v140, 64, v71
	v_cndmask_b32_e64 v146, v140, v21, s[4:5]
	v_ashrrev_i32_e32 v147, 31, v146
	v_lshl_add_u64 v[158:159], v[146:147], 0, s[40:41]
	v_mad_u64_u32 v[160:161], s[96:97], v158, s56, v[50:51]
	v_mad_i32_i24 v161, v159, s56, v161
	global_load_dwordx2 v[140:141], v[160:161], off
	v_mov_b32_e32 v144, v20
	v_mov_b32_e32 v145, v20
	v_cmp_lt_i32_e64 s[96:97], 0, v146
	v_mov_b64_e32 v[142:143], v[144:145]
	s_and_saveexec_b64 s[24:25], s[96:97]
	s_cbranch_execz .Lmy_f_l659
	v_add_co_u32_e32 v142, vcc, 0xfffff000, v160
	s_nop 1
	v_addc_co_u32_e32 v143, vcc, -1, v161, vcc
	global_load_dwordx2 v[142:143], v[142:143], off offset:-2048

.Lmy_f_l669:
	s_or_b64 exec, exec, s[96:97]
	v_lshlrev_b64 v[158:159], 13, v[158:159]
	v_lshl_add_u64 v[158:159], v[52:53], 0, v[158:159]
	v_add_co_u32_e32 v160, vcc, 0x1000, v158
	s_nop 1
	v_addc_co_u32_e32 v161, vcc, 0, v159, vcc
	global_load_dwordx2 v[158:159], v[158:159], off
	s_nop 0
	global_load_dwordx2 v[160:161], v[160:161], off
	v_subrev_u32_e32 v70, s100, v70
	v_add_u32_e32 v71, s100, v71
.Lmy_f_nol2:
	s_lshl_b32 s96, s101, 8
	v_add_u32_e32 v67, s96, v67
	s_andn2_b64 vcc, exec, s[50:51]
	s_cbranch_vccnz .LBB0_655
	s_waitcnt vmcnt(15)
	v_lshlrev_b32_e32 v72, 16, v28
	v_and_b32_e32 v73, 0xffff0000, v28
	v_lshlrev_b32_e32 v76, 16, v30
	v_and_b32_e32 v77, 0xffff0000, v30
	v_lshlrev_b32_e32 v74, 16, v26
	v_and_b32_e32 v75, 0xffff0000, v26
	v_pk_add_f32 v[72:73], v[72:73], v[76:77]
	s_waitcnt vmcnt(13)
	v_lshlrev_b32_e32 v78, 16, v42
	v_pk_fma_f32 v[72:73], v[72:73], 0.5, v[74:75] op_sel_hi:[1,0,1] neg_lo:[0,0,1] neg_hi:[0,0,1]
	v_and_b32_e32 v79, 0xffff0000, v42
	v_pk_fma_f32 v[72:73], v[0:1], v[72:73], v[74:75]
	v_lshlrev_b32_e32 v74, 16, v40
	v_and_b32_e32 v75, 0xffff0000, v40
	v_lshlrev_b32_e32 v76, 16, v38
	v_and_b32_e32 v77, 0xffff0000, v38
	v_pk_add_f32 v[74:75], v[74:75], v[78:79]
	s_waitcnt vmcnt(12)
	v_cvt_f32_f16_e32 v21, v44
	v_pk_fma_f32 v[74:75], v[74:75], 0.5, v[76:77] op_sel_hi:[1,0,1] neg_lo:[0,0,1] neg_hi:[0,0,1]
	v_lshlrev_b32_e32 v80, 16, v31
	v_pk_fma_f32 v[76:77], v[8:9], v[74:75], v[76:77]
	v_lshlrev_b32_e32 v74, 16, v29
	v_and_b32_e32 v75, 0xffff0000, v29
	v_and_b32_e32 v81, 0xffff0000, v31
	v_lshlrev_b32_e32 v78, 16, v27
	v_and_b32_e32 v79, 0xffff0000, v27
	v_pk_add_f32 v[74:75], v[74:75], v[80:81]
	v_cvt_f32_f16_sdwa v84, v44 dst_sel:DWORD dst_unused:UNUSED_PAD src0_sel:WORD_1
	v_pk_fma_f32 v[74:75], v[74:75], 0.5, v[78:79] op_sel_hi:[1,0,1] neg_lo:[0,0,1] neg_hi:[0,0,1]
	v_lshlrev_b32_e32 v82, 16, v43
	v_pk_fma_f32 v[74:75], v[2:3], v[74:75], v[78:79]
	v_lshlrev_b32_e32 v78, 16, v41
	v_and_b32_e32 v79, 0xffff0000, v41
	v_and_b32_e32 v83, 0xffff0000, v43
	v_cvt_f32_f16_e32 v88, v45
	v_lshlrev_b32_e32 v80, 16, v39
	v_and_b32_e32 v81, 0xffff0000, v39
	v_pk_add_f32 v[78:79], v[78:79], v[82:83]
	v_mul_f32_e32 v21, 0xbf1b4598, v21
	v_pk_fma_f32 v[78:79], v[78:79], 0.5, v[80:81] op_sel_hi:[1,0,1] neg_lo:[0,0,1] neg_hi:[0,0,1]
	v_mul_f32_e32 v21, 0x3fb8aa3b, v21
	v_cvt_f32_f16_sdwa v89, v45 dst_sel:DWORD dst_unused:UNUSED_PAD src0_sel:WORD_1
	v_pk_fma_f32 v[78:79], v[10:11], v[78:79], v[80:81]
	v_exp_f32_e32 v80, v21
	v_mul_f32_e32 v21, 0xbf1b4598, v84
	v_mul_f32_e32 v21, 0x3fb8aa3b, v21
	v_lshlrev_b32_e32 v82, 16, v34
	v_and_b32_e32 v83, 0xffff0000, v34
	v_lshlrev_b32_e32 v86, 16, v36
	v_and_b32_e32 v87, 0xffff0000, v36
	v_exp_f32_e32 v81, v21
	v_lshlrev_b32_e32 v84, 16, v32
	v_and_b32_e32 v85, 0xffff0000, v32
	v_pk_add_f32 v[82:83], v[82:83], v[86:87]
	v_mul_f32_e32 v21, 0xbf1b4598, v88
	v_pk_fma_f32 v[82:83], v[82:83], 0.5, v[84:85] op_sel_hi:[1,0,1] neg_lo:[0,0,1] neg_hi:[0,0,1]
	v_mul_f32_e32 v21, 0x3fb8aa3b, v21
	v_pk_fma_f32 v[96:97], v[4:5], v[82:83], v[84:85]
	v_exp_f32_e32 v82, v21
	v_mul_f32_e32 v21, 0xbf1b4598, v89
	v_lshlrev_b32_e32 v84, 16, v35
	v_and_b32_e32 v85, 0xffff0000, v35
	v_lshlrev_b32_e32 v88, 16, v37
	v_and_b32_e32 v89, 0xffff0000, v37
	v_lshlrev_b32_e32 v86, 16, v33
	v_and_b32_e32 v87, 0xffff0000, v33
	v_pk_add_f32 v[84:85], v[84:85], v[88:89]
	s_waitcnt vmcnt(11)
	v_cvt_f32_f16_sdwa v93, v46 dst_sel:DWORD dst_unused:UNUSED_PAD src0_sel:WORD_1
	v_pk_fma_f32 v[84:85], v[84:85], 0.5, v[86:87] op_sel_hi:[1,0,1] neg_lo:[0,0,1] neg_hi:[0,0,1]
	v_cvt_f32_f16_e32 v92, v46
	v_pk_fma_f32 v[94:95], v[6:7], v[84:85], v[86:87]
	v_pk_mul_f32 v[84:85], v[12:13], v[96:97]
	v_pk_mul_f32 v[88:89], v[14:15], v[94:95]
	v_pk_mul_f32 v[86:87], v[84:85], v[84:85]
	v_pk_mul_f32 v[90:91], v[88:89], v[88:89]
	v_add_f32_e32 v83, v86, v87
	v_add_f32_e32 v83, v90, v83
	v_add_f32_e32 v83, v91, v83
	v_cvt_f32_f16_sdwa v99, v47 dst_sel:DWORD dst_unused:UNUSED_PAD src0_sel:WORD_1
	v_cvt_f32_f16_e32 v98, v47
	v_add_f32_dpp v83, v83, v83 quad_perm:[1,0,3,2] row_mask:0xf bank_mask:0xf bound_ctrl:1
	v_mul_f32_e32 v21, 0x3fb8aa3b, v21
	s_bitcmp1_b32 s22, 0
	v_add_f32_dpp v83, v83, v83 quad_perm:[2,3,0,1] row_mask:0xf bank_mask:0xf bound_ctrl:1
	s_cselect_b32 s23, 0x2000, 0
	s_nop 0
	v_add_f32_dpp v83, v83, v83 row_half_mirror row_mask:0xf bank_mask:0xf bound_ctrl:1
	s_nop 1
	v_add_f32_dpp v83, v83, v83 row_mirror row_mask:0xf bank_mask:0xf bound_ctrl:1
	v_max_f32_e32 v83, 0x179abe15, v83
	v_rsq_f32_e32 v86, v83
	v_exp_f32_e32 v83, v21
	v_add_u32_e32 v21, s23, v67
	v_pk_mul_f32 v[90:91], v[84:85], v[86:87] op_sel_hi:[1,0]
	v_pk_mul_f32 v[100:101], v[88:89], v[86:87] op_sel_hi:[1,0]
	v_xor_b32_e32 v85, 0x80000000, v91
	v_xor_b32_e32 v84, 0x80000000, v90
	v_pk_mul_f32 v[88:89], v[90:91], v[92:93]
	v_pk_mul_f32 v[90:91], v[100:101], v[98:99]
	v_pk_add_f32 v[92:93], v[92:93], -1.0 op_sel_hi:[1,0]
	v_pk_add_f32 v[98:99], v[98:99], -1.0 op_sel_hi:[1,0]
	v_pk_fma_f32 v[92:93], v[16:17], v[92:93], 1.0 op_sel_hi:[1,1,0]
	v_pk_fma_f32 v[98:99], v[18:19], v[98:99], 1.0 op_sel_hi:[1,1,0]
	v_xor_b32_e32 v86, 0x80000000, v100
	v_xor_b32_e32 v87, 0x80000000, v101
	v_pk_mul_f32 v[94:95], v[94:95], v[98:99]
	v_pk_mul_f32 v[92:93], v[96:97], v[92:93]
	ds_write_b128 v67, v[80:83]
	ds_write_b128 v67, v[84:87] offset:8192
	ds_write_b128 v67, v[88:91] offset:16384
	ds_write_b128 v67, v[92:95] offset:24576
	ds_write_b128 v67, v[72:75] offset:32768
	ds_write_b128 v21, v[76:79] offset:40960
	v_add_u32_e32 v67, 0x400, v67
	s_waitcnt vmcnt(0)
	v_lshlrev_b32_e32 v72, 16, v142
	v_and_b32_e32 v73, 0xffff0000, v142
	v_lshlrev_b32_e32 v76, 16, v144
	v_and_b32_e32 v77, 0xffff0000, v144
	v_lshlrev_b32_e32 v74, 16, v140
	v_and_b32_e32 v75, 0xffff0000, v140
	v_pk_add_f32 v[72:73], v[72:73], v[76:77]
	s_waitcnt vmcnt(2)
	v_lshlrev_b32_e32 v78, 16, v156
	v_pk_fma_f32 v[72:73], v[72:73], 0.5, v[74:75] op_sel_hi:[1,0,1] neg_lo:[0,0,1] neg_hi:[0,0,1]
	v_and_b32_e32 v79, 0xffff0000, v156
	v_pk_fma_f32 v[72:73], v[0:1], v[72:73], v[74:75]
	v_lshlrev_b32_e32 v74, 16, v154
	v_and_b32_e32 v75, 0xffff0000, v154
	v_lshlrev_b32_e32 v76, 16, v152
	v_and_b32_e32 v77, 0xffff0000, v152
	v_pk_add_f32 v[74:75], v[74:75], v[78:79]
	s_waitcnt vmcnt(1)
	v_cvt_f32_f16_e32 v21, v158
	v_pk_fma_f32 v[74:75], v[74:75], 0.5, v[76:77] op_sel_hi:[1,0,1] neg_lo:[0,0,1] neg_hi:[0,0,1]
	v_lshlrev_b32_e32 v80, 16, v145
	v_pk_fma_f32 v[76:77], v[8:9], v[74:75], v[76:77]
	v_lshlrev_b32_e32 v74, 16, v143
	v_and_b32_e32 v75, 0xffff0000, v143
	v_and_b32_e32 v81, 0xffff0000, v145
	v_lshlrev_b32_e32 v78, 16, v141
	v_and_b32_e32 v79, 0xffff0000, v141
	v_pk_add_f32 v[74:75], v[74:75], v[80:81]
	v_cvt_f32_f16_sdwa v84, v158 dst_sel:DWORD dst_unused:UNUSED_PAD src0_sel:WORD_1
	v_pk_fma_f32 v[74:75], v[74:75], 0.5, v[78:79] op_sel_hi:[1,0,1] neg_lo:[0,0,1] neg_hi:[0,0,1]
	v_lshlrev_b32_e32 v82, 16, v157
	v_pk_fma_f32 v[74:75], v[2:3], v[74:75], v[78:79]
	v_lshlrev_b32_e32 v78, 16, v155
	v_and_b32_e32 v79, 0xffff0000, v155
	v_and_b32_e32 v83, 0xffff0000, v157
	v_cvt_f32_f16_e32 v88, v159
	v_lshlrev_b32_e32 v80, 16, v153
	v_and_b32_e32 v81, 0xffff0000, v153
	v_pk_add_f32 v[78:79], v[78:79], v[82:83]
	v_mul_f32_e32 v21, 0xbf1b4598, v21
	v_pk_fma_f32 v[78:79], v[78:79], 0.5, v[80:81] op_sel_hi:[1,0,1] neg_lo:[0,0,1] neg_hi:[0,0,1]
	v_mul_f32_e32 v21, 0x3fb8aa3b, v21
	v_cvt_f32_f16_sdwa v89, v159 dst_sel:DWORD dst_unused:UNUSED_PAD src0_sel:WORD_1
	v_pk_fma_f32 v[78:79], v[10:11], v[78:79], v[80:81]
	v_exp_f32_e32 v80, v21
	v_mul_f32_e32 v21, 0xbf1b4598, v84
	v_mul_f32_e32 v21, 0x3fb8aa3b, v21
	v_lshlrev_b32_e32 v82, 16, v148
	v_and_b32_e32 v83, 0xffff0000, v148
	v_lshlrev_b32_e32 v86, 16, v150
	v_and_b32_e32 v87, 0xffff0000, v150
	v_exp_f32_e32 v81, v21
	v_lshlrev_b32_e32 v84, 16, v146
	v_and_b32_e32 v85, 0xffff0000, v146
	v_pk_add_f32 v[82:83], v[82:83], v[86:87]
	v_mul_f32_e32 v21, 0xbf1b4598, v88
	v_pk_fma_f32 v[82:83], v[82:83], 0.5, v[84:85] op_sel_hi:[1,0,1] neg_lo:[0,0,1] neg_hi:[0,0,1]
	v_mul_f32_e32 v21, 0x3fb8aa3b, v21
	v_pk_fma_f32 v[96:97], v[4:5], v[82:83], v[84:85]
	v_exp_f32_e32 v82, v21
	v_mul_f32_e32 v21, 0xbf1b4598, v89
	v_lshlrev_b32_e32 v84, 16, v149
	v_and_b32_e32 v85, 0xffff0000, v149
	v_lshlrev_b32_e32 v88, 16, v151
	v_and_b32_e32 v89, 0xffff0000, v151
	v_lshlrev_b32_e32 v86, 16, v147
	v_and_b32_e32 v87, 0xffff0000, v147
	v_pk_add_f32 v[84:85], v[84:85], v[88:89]
	s_waitcnt vmcnt(0)
	v_cvt_f32_f16_sdwa v93, v160 dst_sel:DWORD dst_unused:UNUSED_PAD src0_sel:WORD_1
	v_pk_fma_f32 v[84:85], v[84:85], 0.5, v[86:87] op_sel_hi:[1,0,1] neg_lo:[0,0,1] neg_hi:[0,0,1]
	v_cvt_f32_f16_e32 v92, v160
	v_pk_fma_f32 v[94:95], v[6:7], v[84:85], v[86:87]
	v_pk_mul_f32 v[84:85], v[12:13], v[96:97]
	v_pk_mul_f32 v[88:89], v[14:15], v[94:95]
	v_pk_mul_f32 v[86:87], v[84:85], v[84:85]
	v_pk_mul_f32 v[90:91], v[88:89], v[88:89]
	v_add_f32_e32 v83, v86, v87
	v_add_f32_e32 v83, v90, v83
	v_add_f32_e32 v83, v91, v83
	v_cvt_f32_f16_sdwa v99, v161 dst_sel:DWORD dst_unused:UNUSED_PAD src0_sel:WORD_1
	v_cvt_f32_f16_e32 v98, v161
	v_add_f32_dpp v83, v83, v83 quad_perm:[1,0,3,2] row_mask:0xf bank_mask:0xf bound_ctrl:1
	v_mul_f32_e32 v21, 0x3fb8aa3b, v21
	s_bitcmp1_b32 s22, 0
	v_add_f32_dpp v83, v83, v83 quad_perm:[2,3,0,1] row_mask:0xf bank_mask:0xf bound_ctrl:1
	s_cselect_b32 s23, 0x2000, 0
	s_nop 0
	v_add_f32_dpp v83, v83, v83 row_half_mirror row_mask:0xf bank_mask:0xf bound_ctrl:1
	s_nop 1
	v_add_f32_dpp v83, v83, v83 row_mirror row_mask:0xf bank_mask:0xf bound_ctrl:1
	v_max_f32_e32 v83, 0x179abe15, v83
	v_rsq_f32_e32 v86, v83
	v_exp_f32_e32 v83, v21
	v_add_u32_e32 v21, s23, v67
	v_pk_mul_f32 v[90:91], v[84:85], v[86:87] op_sel_hi:[1,0]
	v_pk_mul_f32 v[100:101], v[88:89], v[86:87] op_sel_hi:[1,0]
	v_xor_b32_e32 v85, 0x80000000, v91
	v_xor_b32_e32 v84, 0x80000000, v90
	v_pk_mul_f32 v[88:89], v[90:91], v[92:93]
	v_pk_mul_f32 v[90:91], v[100:101], v[98:99]
	v_pk_add_f32 v[92:93], v[92:93], -1.0 op_sel_hi:[1,0]
	v_pk_add_f32 v[98:99], v[98:99], -1.0 op_sel_hi:[1,0]
	v_pk_fma_f32 v[92:93], v[16:17], v[92:93], 1.0 op_sel_hi:[1,1,0]
	v_pk_fma_f32 v[98:99], v[18:19], v[98:99], 1.0 op_sel_hi:[1,1,0]
	v_xor_b32_e32 v86, 0x80000000, v100
	v_xor_b32_e32 v87, 0x80000000, v101
	v_pk_mul_f32 v[94:95], v[94:95], v[98:99]
	v_pk_mul_f32 v[92:93], v[96:97], v[92:93]
	ds_write_b128 v67, v[80:83]
	ds_write_b128 v67, v[84:87] offset:8192
	ds_write_b128 v67, v[88:91] offset:16384
	ds_write_b128 v67, v[92:95] offset:24576
	ds_write_b128 v67, v[72:75] offset:32768
	ds_write_b128 v21, v[76:79] offset:40960
	s_lshl_b32 s96, s100, 8
	v_subrev_u32_e32 v67, s96, v67
	s_cmp_gt_u32 s65, 61
	s_cbranch_scc1 .Lmy_f_nol34
	s_add_i32 s101, s101, 32
	s_add_i32 s100, s100, 32
	v_add_u32_e32 v70, s101, v70
	v_subrev_u32_e32 v71, s101, v71
	v_add_u32_e32 v21, 64, v70
	v_subrev_u32_e32 v26, 64, v71
	v_cndmask_b32_e64 v32, v26, v21, s[4:5]
	v_ashrrev_i32_e32 v33, 31, v32
	v_lshl_add_u64 v[44:45], v[32:33], 0, s[40:41]
	v_mad_u64_u32 v[46:47], s[96:97], v44, s56, v[50:51]
	v_mad_i32_i24 v47, v45, s56, v47
	global_load_dwordx2 v[26:27], v[46:47], off
	v_mov_b32_e32 v30, v20
	v_mov_b32_e32 v31, v20
	v_cmp_lt_i32_e64 s[96:97], 0, v32
	v_mov_b64_e32 v[28:29], v[30:31]
	s_and_saveexec_b64 s[24:25], s[96:97]
	s_cbranch_execz .Lmy_f_m659
	v_add_co_u32_e32 v28, vcc, 0xfffff000, v46
	s_nop 1
	v_addc_co_u32_e32 v29, vcc, -1, v47, vcc
	global_load_dwordx2 v[28:29], v[28:29], off offset:-2048

.Lmy_f_nol34:
	s_waitcnt lgkmcnt(0)
	s_bfe_u32 s96, s62, 0x20006
	s_lshl_b32 s100, s96, 11
	v_lshl_add_u32 v72, v224, 2, s100
	s_and_b32 s97, s96, 1
	s_mul_i32 s97, s97, 0x2700
	s_mov_b32 s101, 0x1c000
	s_mov_b32 s100, 0x6100
	s_bitcmp0_b32 s65, 0
	s_cselect_b32 s101, 0xe000, s101
	s_cselect_b32 s100, 0x4e00, s100
	s_cmp_gt_u32 s96, 1
	s_cselect_b32 s100, s100, 0
	s_add_i32 s97, s97, s101
	s_add_i32 s97, s97, s100
	ds_read_b32 v80, v72
	ds_read_b32 v81, v72 offset:256
	ds_read_b32 v82, v72 offset:512
	ds_read_b32 v83, v72 offset:768
	ds_read_b32 v84, v72 offset:1024
	ds_read_b32 v85, v72 offset:1280
	ds_read_b32 v86, v72 offset:1536
	ds_read_b32 v87, v72 offset:1792
	ds_read_b32 v88, v72 offset:8192
	ds_read_b32 v89, v72 offset:8448
	ds_read_b32 v90, v72 offset:8704
	ds_read_b32 v91, v72 offset:8960
	ds_read_b32 v92, v72 offset:9216
	ds_read_b32 v93, v72 offset:9472
	ds_read_b32 v94, v72 offset:9728
	ds_read_b32 v95, v72 offset:9984
	ds_read_b32 v96, v72 offset:32768
	ds_read_b32 v97, v72 offset:33024
	ds_read_b32 v98, v72 offset:33280
	ds_read_b32 v99, v72 offset:33536
	ds_read_b32 v100, v72 offset:33792
	ds_read_b32 v101, v72 offset:34048
	ds_read_b32 v102, v72 offset:34304
	ds_read_b32 v103, v72 offset:34560
	v_and_b32_e32 v74, 3, v224
	v_bfe_u32 v75, v224, 2, 2
	v_lshrrev_b32_e32 v76, 4, v224
	v_lshlrev_b32_e32 v74, 2, v74
	v_lshl_add_u32 v74, v75, 8, v74
	v_lshl_add_u32 v74, v76, 10, v74
	s_add_i32 s100, s97, 0x0
	v_add_u32_e32 v74, s100, v74
	v_xor_b32_e32 v76, 0, v75
	v_xor_b32_e32 v77, 1, v75
	v_xor_b32_e32 v78, 2, v75
	v_xor_b32_e32 v79, 3, v75
	v_lshl_add_u32 v76, v76, 4, v74
	v_lshl_add_u32 v77, v77, 4, v74
	v_lshl_add_u32 v78, v78, 4, v74
	v_lshl_add_u32 v79, v79, 4, v74
	s_waitcnt lgkmcnt(15)
	v_mov_b32_e32 v104, v80
	v_mul_f32_e32 v105, v104, v81
	v_mul_f32_e32 v106, v105, v82
	v_mul_f32_e32 v107, v106, v83
	v_mul_f32_e32 v108, v107, v84
	v_mul_f32_e32 v109, v108, v85
	v_mul_f32_e32 v110, v109, v86
	v_mul_f32_e32 v111, v110, v87
	v_mov_b32_e32 v112, v88
	s_waitcnt lgkmcnt(14)
	v_mul_f32_e32 v113, v104, v89
	s_waitcnt lgkmcnt(13)
	v_mul_f32_e32 v114, v105, v90
	s_waitcnt lgkmcnt(12)
	v_mul_f32_e32 v115, v106, v91
	s_waitcnt lgkmcnt(11)
	v_mul_f32_e32 v116, v107, v92
	s_waitcnt lgkmcnt(10)
	v_mul_f32_e32 v117, v108, v93
	s_waitcnt lgkmcnt(9)
	v_mul_f32_e32 v118, v109, v94
	s_waitcnt lgkmcnt(8)
	v_mul_f32_e32 v119, v110, v95
	s_waitcnt lgkmcnt(7)
	v_mul_f32_e32 v120, v104, v96
	s_waitcnt lgkmcnt(6)
	v_mul_f32_e32 v121, v105, v97
	s_waitcnt lgkmcnt(5)
	v_mul_f32_e32 v122, v106, v98
	s_waitcnt lgkmcnt(4)
	v_mul_f32_e32 v123, v107, v99
	s_waitcnt lgkmcnt(3)
	v_mul_f32_e32 v124, v108, v100
	s_waitcnt lgkmcnt(2)
	v_mul_f32_e32 v125, v109, v101
	s_waitcnt lgkmcnt(1)
	v_mul_f32_e32 v126, v110, v102
	s_waitcnt lgkmcnt(0)
	v_mul_f32_e32 v127, v111, v103
	ds_write_b32 v76, v112
	ds_write_b32 v77, v113
	ds_write_b32 v78, v114
	ds_write_b32 v79, v115
	ds_write_b32 v76, v116 offset:64
	ds_write_b32 v77, v117 offset:64
	ds_write_b32 v78, v118 offset:64
	ds_write_b32 v79, v119 offset:64
	ds_write_b32 v76, v120 offset:128
	ds_write_b32 v77, v121 offset:128
	ds_write_b32 v78, v122 offset:128
	ds_write_b32 v79, v123 offset:128
	ds_write_b32 v76, v124 offset:192
	ds_write_b32 v77, v125 offset:192
	ds_write_b32 v78, v126 offset:192
	ds_write_b32 v79, v127 offset:192

.Lmy_ck_drE_h:
	s_waitcnt lgkmcnt(0)
	s_bfe_u32 s96, s62, 0x20006
	s_and_b32 s97, s96, 1
	s_mul_i32 s97, s97, 0x2700
	s_mov_b32 s101, 0x1c000
	s_mov_b32 s100, 0x6100
	s_bitcmp0_b32 s65, 0
	s_cselect_b32 s101, 0xe000, s101
	s_cselect_b32 s100, 0x4e00, s100
	s_cmp_gt_u32 s96, 1
	s_cselect_b32 s100, s100, 0
	s_add_i32 s97, s97, s101
	s_add_i32 s97, s97, s100
	s_mov_b32 s96, s97
	v_and_b32_e32 v72, 3, v233
	v_lshrrev_b32_e32 v73, 2, v233
	v_lshlrev_b32_e32 v72, 2, v72
	v_lshl_add_u32 v72, v73, 8, v72
	v_lshl_add_u32 v72, v234, 6, v72
	s_add_i32 s97, s96, 0x1000
	v_add_u32_e32 v78, s97, v72
	v_xor_b32_e32 v79, v224, v234
	v_lshl_add_u32 v79, v79, 4, s96
	ds_read_b128 v[96:99], v79
	ds_read_b128 v[100:103], v79 offset:1024
	ds_read_b128 v[104:107], v79 offset:2048
	ds_read_b128 v[108:111], v79 offset:3072
	ds_read_b32 v80, v78
	ds_read_b32 v81, v78 offset:16
	ds_read_b32 v82, v78 offset:32
	ds_read_b32 v83, v78 offset:48
	ds_read_b32 v84, v78 offset:1024
	ds_read_b32 v85, v78 offset:1040
	ds_read_b32 v86, v78 offset:1056
	ds_read_b32 v87, v78 offset:1072
	ds_read_b32 v88, v78 offset:2048
	ds_read_b32 v89, v78 offset:2064
	ds_read_b32 v90, v78 offset:2080
	ds_read_b32 v91, v78 offset:2096
	ds_read_b32 v92, v78 offset:3072
	ds_read_b32 v93, v78 offset:3088
	ds_read_b32 v94, v78 offset:3104
	ds_read_b32 v95, v78 offset:3120
	v_lshl_add_u32 v74, v224, 2, s96
	ds_write_b32 v74, v235 offset:9728
	v_add_u32_e32 v75, -1, v233
	v_mov_b32_e32 v76, -1
	v_cndmask_b32_e64 v75, v76, v75, s[98:99]
	v_cmp_lt_u32_e64 s[100:101], 7, v233
	v_add_u32_e32 v76, -8, v233
	v_and_b32_e32 v77, 1, v234
	v_cndmask_b32_e64 v75, v75, v76, s[100:101]
	v_lshlrev_b32_e32 v77, 2, v77
	v_sub_u32_e32 v76, v75, v77
	v_lshlrev_b32_e32 v77, 2, v234
	v_sub_u32_e32 v77, v233, v77
	v_add_u32_e32 v77, -1, v77
	s_waitcnt lgkmcnt(15)
	v_mfma_f32_16x16x4_f32 v[244:247], v80, v96, 0
	v_mfma_f32_16x16x4_f32 v[240:243], v81, v97, 0
	s_waitcnt lgkmcnt(14)
	v_mfma_f32_16x16x4_f32 v[244:247], v82, v98, v[244:247]
	s_waitcnt lgkmcnt(13)
	v_mfma_f32_16x16x4_f32 v[240:243], v83, v99, v[240:243]
	s_waitcnt lgkmcnt(12)
	v_mfma_f32_16x16x4_f32 v[244:247], v84, v100, v[244:247]
	s_waitcnt lgkmcnt(11)
	v_mfma_f32_16x16x4_f32 v[240:243], v85, v101, v[240:243]
	s_waitcnt lgkmcnt(10)
	v_mfma_f32_16x16x4_f32 v[244:247], v86, v102, v[244:247]
	s_waitcnt lgkmcnt(9)
	v_mfma_f32_16x16x4_f32 v[240:243], v87, v103, v[240:243]
	s_waitcnt lgkmcnt(8)
	v_mfma_f32_16x16x4_f32 v[244:247], v88, v104, v[244:247]
	s_waitcnt lgkmcnt(7)
	v_mfma_f32_16x16x4_f32 v[240:243], v89, v105, v[240:243]
	s_waitcnt lgkmcnt(6)
	v_mfma_f32_16x16x4_f32 v[244:247], v90, v106, v[244:247]
	s_waitcnt lgkmcnt(5)
	v_mfma_f32_16x16x4_f32 v[240:243], v91, v107, v[240:243]
	s_waitcnt lgkmcnt(4)
	v_mfma_f32_16x16x4_f32 v[244:247], v92, v108, v[244:247]
	s_waitcnt lgkmcnt(3)
	v_mfma_f32_16x16x4_f32 v[240:243], v93, v109, v[240:243]
	s_waitcnt lgkmcnt(2)
	v_mfma_f32_16x16x4_f32 v[244:247], v94, v110, v[244:247]
	s_waitcnt lgkmcnt(1)
	v_mfma_f32_16x16x4_f32 v[240:243], v95, v111, v[240:243]
	s_nop 9
	v_add_f32_e32 v244, v244, v240
	v_add_f32_e32 v245, v245, v241
	v_add_f32_e32 v246, v246, v242
	v_add_f32_e32 v247, v247, v243
	v_cmp_le_i32_e64 s[96:97], 0, v76
	v_cmp_le_i32_e64 s[100:101], 1, v76
	s_nop 0
	v_cndmask_b32_e64 v128, 0, v244, s[96:97]
	v_cndmask_b32_e64 v129, 0, v245, s[100:101]
	v_cmp_le_i32_e64 s[96:97], 2, v76
	v_cmp_le_i32_e64 s[100:101], 3, v76
	s_nop 0
	v_cndmask_b32_e64 v130, 0, v246, s[96:97]
	v_cndmask_b32_e64 v131, 0, v247, s[100:101]
	s_bfe_u32 s96, s62, 0x20006
	s_and_b32 s97, s96, 1
	s_mul_i32 s97, s97, 0x2700
	s_mov_b32 s101, 0x1c000
	s_mov_b32 s100, 0x6100
	s_bitcmp0_b32 s65, 0
	s_cselect_b32 s101, 0xe000, s101
	s_cselect_b32 s100, 0x4e00, s100
	s_cmp_gt_u32 s96, 1
	s_cselect_b32 s100, s100, 0
	s_add_i32 s97, s97, s101
	s_add_i32 s97, s97, s100
	v_xor_b32_e32 v74, v224, v234
	v_lshl_add_u32 v74, v74, 4, s97
	ds_write_b128 v74, v[128:131] offset:8448
	v_lshlrev_b32_e32 v75, 7, v234
	v_lshl_add_u32 v75, v233, 2, v75
	v_add_u32_e32 v75, s97, v75
	v_cmp_le_i32_e64 s[96:97], 0, v77
	v_cmp_le_i32_e64 s[100:101], 1, v77
	s_nop 0
	v_cndmask_b32_e64 v132, 0, v244, s[96:97]
	v_cndmask_b32_e64 v133, 0, v245, s[100:101]
	v_cmp_le_i32_e64 s[96:97], 2, v77
	v_cmp_le_i32_e64 s[100:101], 3, v77
	s_nop 0
	v_cndmask_b32_e64 v134, 0, v246, s[96:97]
	v_cndmask_b32_e64 v135, 0, v247, s[100:101]
	s_mov_b64 exec, 0x00ff00ff
	ds_write_b32 v75, v132 offset:9472
	ds_write_b32 v75, v133 offset:9504
	ds_write_b32 v75, v134 offset:9536
	ds_write_b32 v75, v135 offset:9568
	s_mov_b64 exec, -1
	s_branch .LBB0_655
